# attention loop: waves 4-7 run half a KV tile behind waves 0-3 (their per-tile barrier moved to the loop top, DMA issued mid-iteration)
# speedup vs baseline: 1.0037x; 1.0003x over previous
; #define AT_LDK(bufoff, kbi) do { _Pragma("unroll") for (int s_ = 0; s_ < 4; ++s_) kf[s_] = *(const LAS bf16x8*)(kl_ + (bufoff) + ((2 * s_) * 64 + 32 * (kbi)) * 16); } while (0)
; #define AT_LDV(bufoff, kbi) do { _Pragma("unroll") for (int db_ = 0; db_ < 4; ++db_) { vf[2 * db_] = *(const LAS bf16x8*)(vl_ + (bufoff) + ((4 * (kbi)) * 128 + 32 * db_) * 16); vf[2 * db_ + 1] = *(const LAS bf16x8*)(vl_ + (bufoff) + ((4 * (kbi) + 2) * 128 + 32 * db_) * 16); } } while (0)
; #define AT_MQK(dst) do { dst = __builtin_amdgcn_mfma_f32_32x32x16_bf16(kf[0], qf[0], negm, 0, 0, 0); _Pragma("unroll") for (int s_ = 1; s_ < 4; ++s_) dst = __builtin_amdgcn_mfma_f32_32x32x16_bf16(kf[s_], qf[s_], dst, 0, 0, 0); } while (0)
; #define AT_MPV(pk0_, pk1_) do { _Pragma("unroll") for (int db_ = 0; db_ < 4; ++db_) { o[db_] = __builtin_amdgcn_mfma_f32_32x32x16_bf16(pk0_, vf[2 * db_], o[db_], 0, 0, 0); o[db_] = __builtin_amdgcn_mfma_f32_32x32x16_bf16(pk1_, vf[2 * db_ + 1], o[db_], 0, 0, 0); } } while (0)
; #define AT_SM(src, pk0_, pk1_) do { float ls_ = 0.f; _Pragma("unroll") for (int r_ = 0; r_ < 16; ++r_) { src[r_] = __builtin_amdgcn_exp2f(src[r_]); ls_ += src[r_]; } lsum += ls_; pk0_ = pack8(src, 0); pk1_ = pack8(src, 8); } while (0)
; #define AT_SB() __builtin_amdgcn_sched_barrier(0)
; __device__ __forceinline__ void attn_unit(const Params& p, int l, int b, int h, int qpos0, int kbeg, int nkt, int grow0, float lam, float lam_init, unsigned char* lds, int wid0) {
;     ...
;     for (int it = 0; it < nkt; ++it) {
;         AT_LDK(bo, 1); AT_LDV((it ? bop : bo), 1); AT_SB();
;         AT_SM(Sc, pB0, pB1); AT_SB();
;         __builtin_amdgcn_s_setprio(3); AT_MQK(Sn); AT_MPV(pA0, pA1); __builtin_amdgcn_s_setprio(0); AT_SB();
;         if (it + 2 < nkt) asm volatile("s_waitcnt vmcnt(4)" ::: "memory"); else asm volatile("s_waitcnt vmcnt(0)" ::: "memory");
;         __syncthreads();
;         if (it + 3 < nkt) AT_DMA(kt0 + it + 3, (bop >> 15));
;         if (it + 1 < nkt) AT_LDK(bo1, 0);
;         AT_LDV(bo, 0); AT_SB();
;         AT_SM(Sn, pA0, pA1); AT_SB();
;         __builtin_amdgcn_s_setprio(3); if (it + 1 < nkt) AT_MQK(Sc);
;         AT_MPV(pB0, pB1); __builtin_amdgcn_s_setprio(0); AT_SB();
;         const int tb = bop; bop = bo; bo = bo1; bo1 = bo2; bo2 = tb;
;     }
.LBB0_177:
	s_mov_b32 s83, s82
	v_add_u32_e32 v236, s65, v142
	v_add_u32_e32 v235, s55, v138
	s_cmp_lt_u32 s31, 0x2000
	s_cbranch_scc1 .Lattn_topx
	s_waitcnt lgkmcnt(4)
	s_waitcnt vmcnt(4)
	s_barrier
.Lattn_topx:
	s_setprio 3
	s_waitcnt lgkmcnt(10)
	v_mfma_f32_32x32x16_bf16 v[0:15], v[114:117], v[174:177], v[0:15]
	ds_read_b128 v[174:177], v236 offset:16384
	v_exp_f32_e32 v140, v80
	v_exp_f32_e32 v141, v81
	v_mfma_f32_32x32x16_bf16 v[16:31], v[114:117], v[178:181], v[16:31]
	ds_read_b128 v[178:181], v236 offset:16896
	v_exp_f32_e32 v143, v82
	v_exp_f32_e32 v144, v83
	v_add_f32_e32 v139, v139, v140
	s_waitcnt lgkmcnt(10)
	v_mfma_f32_32x32x16_bf16 v[32:47], v[114:117], v[182:185], v[32:47]
	ds_read_b128 v[182:185], v236 offset:17408
	v_exp_f32_e32 v145, v84
	v_exp_f32_e32 v146, v85
	v_add_f32_e32 v139, v139, v141
	v_mfma_f32_32x32x16_bf16 v[48:63], v[114:117], v[186:189], v[48:63]
	ds_read_b128 v[186:189], v236 offset:17920
	v_exp_f32_e32 v147, v86
	v_exp_f32_e32 v148, v87
	v_add_f32_e32 v139, v139, v143
	s_waitcnt lgkmcnt(10)
	v_mfma_f32_32x32x16_bf16 v[0:15], v[118:121], v[190:193], v[0:15]
	ds_read_b128 v[190:193], v236 offset:20480
	v_exp_f32_e32 v149, v88
	v_exp_f32_e32 v150, v89
	v_add_f32_e32 v139, v139, v144
	v_mfma_f32_32x32x16_bf16 v[16:31], v[118:121], v[194:197], v[16:31]
	ds_read_b128 v[194:197], v236 offset:20992
	v_exp_f32_e32 v151, v90
	v_exp_f32_e32 v152, v91
	v_add_f32_e32 v139, v139, v145
	s_waitcnt lgkmcnt(10)
	v_mfma_f32_32x32x16_bf16 v[32:47], v[118:121], v[198:201], v[32:47]
	ds_read_b128 v[198:201], v236 offset:21504
	v_exp_f32_e32 v153, v92
	v_exp_f32_e32 v154, v93
	v_add_f32_e32 v139, v139, v146
	v_mfma_f32_32x32x16_bf16 v[48:63], v[118:121], v[202:205], v[48:63]
	ds_read_b128 v[202:205], v236 offset:22016
	v_exp_f32_e32 v155, v94
	v_exp_f32_e32 v156, v95
	v_add_f32_e32 v139, v139, v147
	s_waitcnt lgkmcnt(10)
	v_mfma_f32_32x32x16_bf16 v[80:95], v[158:161], v[110:113], v[64:79]
	v_cvt_pk_bf16_f32 v122, v140, v141
	v_cvt_pk_bf16_f32 v123, v143, v144
	v_add_f32_e32 v139, v139, v148
	v_add_f32_e32 v139, v139, v149
	v_mfma_f32_32x32x16_bf16 v[80:95], v[162:165], v[102:105], v[80:95]
	v_cvt_pk_bf16_f32 v124, v145, v146
	v_cvt_pk_bf16_f32 v125, v147, v148
	v_add_f32_e32 v139, v139, v150
	v_add_f32_e32 v139, v139, v151
	s_waitcnt lgkmcnt(8)
	v_mfma_f32_32x32x16_bf16 v[80:95], v[166:169], v[106:109], v[80:95]
	v_cvt_pk_bf16_f32 v126, v149, v150
	v_cvt_pk_bf16_f32 v127, v151, v152
	v_add_f32_e32 v139, v139, v152
	v_add_f32_e32 v139, v139, v153
	v_mfma_f32_32x32x16_bf16 v[80:95], v[170:173], v[98:101], v[80:95]
	v_cvt_pk_bf16_f32 v128, v153, v154
	v_cvt_pk_bf16_f32 v129, v155, v156
	v_add_f32_e32 v139, v139, v154
	v_add_f32_e32 v139, v139, v155
	v_add_f32_e32 v139, v139, v156
	s_setprio 0
	s_cmp_ge_u32 s31, 0x2000
	s_cbranch_scc1 .Lattn_midy
	s_waitcnt vmcnt(4)
	s_barrier
.Lattn_midy:
	s_cmp_lt_u32 s74, s73
	s_cbranch_scc0 .LBB0_179
	v_lshl_add_u64 v[114:115], v[136:137], 0, s[0:1]
	s_mov_b64 s[94:95], 0x6410000
	s_and_b32 s82, s83, 0xffff8000
	v_lshl_add_u64 v[116:117], v[114:115], 0, s[94:95]
	s_mov_b64 s[94:95], 0x6410400
	s_add_i32 s82, s31, s82
	v_lshl_add_u64 v[118:119], v[114:115], 0, s[94:95]
	s_mov_b64 s[94:95], 0x4210000
	s_add_i32 vcc_lo, s82, 0x400
	v_lshl_add_u64 v[120:121], v[114:115], 0, s[94:95]
	s_mov_b64 s[94:95], 0x4210400
	s_mov_b32 m0, s82
	s_add_i32 s93, s82, 0x4000
	v_lshl_add_u64 v[114:115], v[114:115], 0, s[94:95]
	global_load_lds_dwordx4 v[120:121], off
	s_mov_b32 m0, vcc_lo
	s_add_i32 s84, s82, 0x4400
	global_load_lds_dwordx4 v[114:115], off
	s_mov_b32 m0, s93
	s_nop 0
	global_load_lds_dwordx4 v[116:117], off
	s_mov_b32 m0, s84
	s_nop 0
	global_load_lds_dwordx4 v[118:119], off
.LBB0_179:
	ds_read_b128 v[158:161], v235
	ds_read_b128 v[162:165], v235 offset:2048
	ds_read_b128 v[166:169], v235 offset:4096
	ds_read_b128 v[170:173], v235 offset:6144
	s_add_i32 s74, s74, 1
	s_setprio 3
	s_waitcnt lgkmcnt(10)
	v_mfma_f32_32x32x16_bf16 v[0:15], v[122:125], v[174:177], v[0:15]
	ds_read_b128 v[174:177], v236 offset:24576
	v_exp_f32_e32 v140, v80
	v_exp_f32_e32 v141, v81
	v_mfma_f32_32x32x16_bf16 v[16:31], v[122:125], v[178:181], v[16:31]
	ds_read_b128 v[178:181], v236 offset:25088
	v_exp_f32_e32 v143, v82
	v_exp_f32_e32 v144, v83
	v_add_f32_e32 v139, v139, v140
	s_waitcnt lgkmcnt(10)
	v_mfma_f32_32x32x16_bf16 v[32:47], v[122:125], v[182:185], v[32:47]
	ds_read_b128 v[182:185], v236 offset:25600
	v_exp_f32_e32 v145, v84
	v_exp_f32_e32 v146, v85
	v_add_f32_e32 v139, v139, v141
	v_mfma_f32_32x32x16_bf16 v[48:63], v[122:125], v[186:189], v[48:63]
	ds_read_b128 v[186:189], v236 offset:26112
	v_exp_f32_e32 v147, v86
	v_exp_f32_e32 v148, v87
	v_add_f32_e32 v139, v139, v143
	s_waitcnt lgkmcnt(10)
	v_mfma_f32_32x32x16_bf16 v[0:15], v[126:129], v[190:193], v[0:15]
	ds_read_b128 v[190:193], v236 offset:28672
	v_exp_f32_e32 v149, v88
	v_exp_f32_e32 v150, v89
	v_add_f32_e32 v139, v139, v144
	v_mfma_f32_32x32x16_bf16 v[16:31], v[126:129], v[194:197], v[16:31]
	ds_read_b128 v[194:197], v236 offset:29184
	v_exp_f32_e32 v151, v90
	v_exp_f32_e32 v152, v91
	v_add_f32_e32 v139, v139, v145
	s_waitcnt lgkmcnt(10)
	v_mfma_f32_32x32x16_bf16 v[32:47], v[126:129], v[198:201], v[32:47]
	ds_read_b128 v[198:201], v236 offset:29696
	v_exp_f32_e32 v153, v92
	v_exp_f32_e32 v154, v93
	v_add_f32_e32 v139, v139, v146
	v_mfma_f32_32x32x16_bf16 v[48:63], v[126:129], v[202:205], v[48:63]
	ds_read_b128 v[202:205], v236 offset:30208
	v_exp_f32_e32 v155, v94
	v_exp_f32_e32 v156, v95
	v_add_f32_e32 v139, v139, v147
	s_waitcnt lgkmcnt(10)
	v_mfma_f32_32x32x16_bf16 v[80:95], v[158:161], v[110:113], v[64:79]
	ds_read_b128 v[158:161], v235 offset:512
	v_cvt_pk_bf16_f32 v114, v140, v141
	v_cvt_pk_bf16_f32 v115, v143, v144
	v_add_f32_e32 v139, v139, v148
	v_add_f32_e32 v139, v139, v149
	v_mfma_f32_32x32x16_bf16 v[80:95], v[162:165], v[102:105], v[80:95]
	ds_read_b128 v[162:165], v235 offset:2560
	v_cvt_pk_bf16_f32 v116, v145, v146
	v_cvt_pk_bf16_f32 v117, v147, v148
	v_add_f32_e32 v139, v139, v150
	v_add_f32_e32 v139, v139, v151
	s_waitcnt lgkmcnt(10)
	v_mfma_f32_32x32x16_bf16 v[80:95], v[166:169], v[106:109], v[80:95]
	ds_read_b128 v[166:169], v235 offset:4608
	v_cvt_pk_bf16_f32 v118, v149, v150
	v_cvt_pk_bf16_f32 v119, v151, v152
	v_add_f32_e32 v139, v139, v152
	v_add_f32_e32 v139, v139, v153
	v_mfma_f32_32x32x16_bf16 v[80:95], v[170:173], v[98:101], v[80:95]
	ds_read_b128 v[170:173], v235 offset:6656
	v_cvt_pk_bf16_f32 v120, v153, v154
	v_cvt_pk_bf16_f32 v121, v155, v156
	v_add_f32_e32 v139, v139, v154
	v_add_f32_e32 v139, v139, v155
	v_add_f32_e32 v139, v139, v156
	s_setprio 0
	s_add_u32 s0, s0, 0x4000
	s_addc_u32 s1, s1, 0
	s_cmp_eq_u32 s75, s0
	s_cbranch_scc1 .LBB0_181
	s_mov_b32 s82, s65
	s_mov_b32 s65, s55
	s_mov_b32 s55, s54
	s_mov_b32 s54, s83
	s_branch .LBB0_177
